# accumulator zeroing between GEMM tiles with packed 64-bit moves (half the VALU issue slots), on top of v11
# baseline (speedup 1.0000x reference)
;     __device__ __forceinline__ bool next(int i, UnitD& u) const { Unit t; if (!so.next(i, t)) return false; u.A = A + (size_t)t.pm * tsA; u.B = B + (size_t)t.pn * tsB; u.nt = nt; u.pm = t.pm; u.pn = t.pn; u.tag = 0; return true; }
; template <class Epi, class Sched>
; __device__ __forceinline__ void gemm_stream(LAS unsigned char* lds, const int lda, const int ldb, const Sched& S, const Epi& E, const int wv) {
;     ...
;     for (;;) {
;         const bool has_next = S.next(ui + 1, nxt);
;         const char* nA = has_next ? nxt.A : cA; const char* nB = has_next ? nxt.B : cB;
;         const int nt = cur.nt;
;         for (int t = 0; t < nt; t += 2) {
;             const bool last = (t == nt - 2);
;             const char* a1 = cA + (size_t)(t + 1) * kstep;
;             const char* a2 = last ? nA : cA + (size_t)(t + 2) * kstep; const char* b2 = last ? nB : cB + (size_t)(t + 2) * kstep;
;             const char* a3 = a2 + kstep; const char* b3 = b2 + kstep;
;     ...
; #pragma unroll
;         for (int a = 0; a < 2; ++a)
; #pragma unroll
;             for (int b = 0; b < 2; ++b)
; #pragma unroll
;                 for (int m = 0; m < 4; ++m)
; #pragma unroll
;                     for (int n = 0; n < 2; ++n) acc[a][b][m][n] = (f32x4){0.f, 0.f, 0.f, 0.f};
;         cur = nxt; cA = nA; cB = nB; ++ui;
.LBB0_221:
	s_and_b64 s[34:35], s[24:25], exec
	s_cselect_b32 s3, s17, s29
	s_cselect_b32 s21, s16, s28
	s_cselect_b32 s23, s19, s31
	s_cselect_b32 s27, s18, s30
	s_add_u32 s28, s28, 0x80080
	s_addc_u32 s29, s29, 0
	s_add_u32 s33, s30, 0x100
	v_mov_b32_e32 v0, 0
	s_addc_u32 s36, s31, 0
	s_mov_b32 s37, -2
	v_mov_b32_e32 v1, v0
	v_pk_mov_b32 v[2:3], v[0:1], v[0:1] op_sel:[0,0]
	v_pk_mov_b32 v[4:5], v[0:1], v[0:1] op_sel:[0,0]
	v_pk_mov_b32 v[6:7], v[0:1], v[0:1] op_sel:[0,0]
	v_pk_mov_b32 v[16:17], v[0:1], v[0:1] op_sel:[0,0]
	v_pk_mov_b32 v[18:19], v[0:1], v[0:1] op_sel:[0,0]
	v_pk_mov_b32 v[20:21], v[0:1], v[0:1] op_sel:[0,0]
	v_pk_mov_b32 v[22:23], v[0:1], v[0:1] op_sel:[0,0]
	v_pk_mov_b32 v[32:33], v[0:1], v[0:1] op_sel:[0,0]
	v_pk_mov_b32 v[34:35], v[0:1], v[0:1] op_sel:[0,0]
	v_pk_mov_b32 v[36:37], v[0:1], v[0:1] op_sel:[0,0]
	v_pk_mov_b32 v[38:39], v[0:1], v[0:1] op_sel:[0,0]
	v_pk_mov_b32 v[48:49], v[0:1], v[0:1] op_sel:[0,0]
	v_pk_mov_b32 v[50:51], v[0:1], v[0:1] op_sel:[0,0]
	v_pk_mov_b32 v[52:53], v[0:1], v[0:1] op_sel:[0,0]
	v_pk_mov_b32 v[54:55], v[0:1], v[0:1] op_sel:[0,0]
	v_pk_mov_b32 v[8:9], v[0:1], v[0:1] op_sel:[0,0]
	v_pk_mov_b32 v[10:11], v[0:1], v[0:1] op_sel:[0,0]
	v_pk_mov_b32 v[12:13], v[0:1], v[0:1] op_sel:[0,0]
	v_pk_mov_b32 v[14:15], v[0:1], v[0:1] op_sel:[0,0]
	v_pk_mov_b32 v[24:25], v[0:1], v[0:1] op_sel:[0,0]
	v_pk_mov_b32 v[26:27], v[0:1], v[0:1] op_sel:[0,0]
	v_pk_mov_b32 v[28:29], v[0:1], v[0:1] op_sel:[0,0]
	v_pk_mov_b32 v[30:31], v[0:1], v[0:1] op_sel:[0,0]
	v_pk_mov_b32 v[40:41], v[0:1], v[0:1] op_sel:[0,0]
	v_pk_mov_b32 v[42:43], v[0:1], v[0:1] op_sel:[0,0]
	v_pk_mov_b32 v[44:45], v[0:1], v[0:1] op_sel:[0,0]
	v_pk_mov_b32 v[46:47], v[0:1], v[0:1] op_sel:[0,0]
	v_pk_mov_b32 v[56:57], v[0:1], v[0:1] op_sel:[0,0]
	v_pk_mov_b32 v[58:59], v[0:1], v[0:1] op_sel:[0,0]
	v_pk_mov_b32 v[60:61], v[0:1], v[0:1] op_sel:[0,0]
	v_pk_mov_b32 v[62:63], v[0:1], v[0:1] op_sel:[0,0]
	v_pk_mov_b32 v[64:65], v[0:1], v[0:1] op_sel:[0,0]
	v_pk_mov_b32 v[66:67], v[0:1], v[0:1] op_sel:[0,0]
	v_pk_mov_b32 v[68:69], v[0:1], v[0:1] op_sel:[0,0]
	v_pk_mov_b32 v[70:71], v[0:1], v[0:1] op_sel:[0,0]
	v_pk_mov_b32 v[80:81], v[0:1], v[0:1] op_sel:[0,0]
	v_pk_mov_b32 v[82:83], v[0:1], v[0:1] op_sel:[0,0]
	v_pk_mov_b32 v[84:85], v[0:1], v[0:1] op_sel:[0,0]
	v_pk_mov_b32 v[86:87], v[0:1], v[0:1] op_sel:[0,0]
	v_pk_mov_b32 v[96:97], v[0:1], v[0:1] op_sel:[0,0]
	v_pk_mov_b32 v[98:99], v[0:1], v[0:1] op_sel:[0,0]
	v_pk_mov_b32 v[100:101], v[0:1], v[0:1] op_sel:[0,0]
	v_pk_mov_b32 v[102:103], v[0:1], v[0:1] op_sel:[0,0]
	v_pk_mov_b32 v[112:113], v[0:1], v[0:1] op_sel:[0,0]
	v_pk_mov_b32 v[114:115], v[0:1], v[0:1] op_sel:[0,0]
	v_pk_mov_b32 v[116:117], v[0:1], v[0:1] op_sel:[0,0]
	v_pk_mov_b32 v[118:119], v[0:1], v[0:1] op_sel:[0,0]
	v_pk_mov_b32 v[72:73], v[0:1], v[0:1] op_sel:[0,0]
	v_pk_mov_b32 v[74:75], v[0:1], v[0:1] op_sel:[0,0]
	v_pk_mov_b32 v[76:77], v[0:1], v[0:1] op_sel:[0,0]
	v_pk_mov_b32 v[78:79], v[0:1], v[0:1] op_sel:[0,0]
	v_pk_mov_b32 v[88:89], v[0:1], v[0:1] op_sel:[0,0]
	v_pk_mov_b32 v[90:91], v[0:1], v[0:1] op_sel:[0,0]
	v_pk_mov_b32 v[92:93], v[0:1], v[0:1] op_sel:[0,0]
	v_pk_mov_b32 v[94:95], v[0:1], v[0:1] op_sel:[0,0]
	v_pk_mov_b32 v[104:105], v[0:1], v[0:1] op_sel:[0,0]
	v_pk_mov_b32 v[106:107], v[0:1], v[0:1] op_sel:[0,0]
	v_pk_mov_b32 v[108:109], v[0:1], v[0:1] op_sel:[0,0]
	v_pk_mov_b32 v[110:111], v[0:1], v[0:1] op_sel:[0,0]
	v_pk_mov_b32 v[120:121], v[0:1], v[0:1] op_sel:[0,0]
	v_pk_mov_b32 v[122:123], v[0:1], v[0:1] op_sel:[0,0]
	v_pk_mov_b32 v[124:125], v[0:1], v[0:1] op_sel:[0,0]
	v_pk_mov_b32 v[126:127], v[0:1], v[0:1] op_sel:[0,0]

;     __device__ __forceinline__ bool next(int i, UnitD& u) const { Unit t; if (!so.next(i, t)) return false; u.A = A + (size_t)t.pm * tsA; u.B = B + (size_t)t.pn * tsB; u.nt = nt; u.pm = t.pm; u.pn = t.pn; u.tag = 0; return true; }
; template <class Epi, class Sched>
; __device__ __forceinline__ void gemm_stream(LAS unsigned char* lds, const int lda, const int ldb, const Sched& S, const Epi& E, const int wv) {
;     ...
;     for (;;) {
;         const bool has_next = S.next(ui + 1, nxt);
;         const char* nA = has_next ? nxt.A : cA; const char* nB = has_next ? nxt.B : cB;
;         const int nt = cur.nt;
;         for (int t = 0; t < nt; t += 2) {
;             const bool last = (t == nt - 2);
;             const char* a1 = cA + (size_t)(t + 1) * kstep;
;             const char* a2 = last ? nA : cA + (size_t)(t + 2) * kstep; const char* b2 = last ? nB : cB + (size_t)(t + 2) * kstep;
;             const char* a3 = a2 + kstep; const char* b3 = b2 + kstep;
;     ...
; #pragma unroll
;         for (int a = 0; a < 2; ++a)
; #pragma unroll
;             for (int b = 0; b < 2; ++b)
; #pragma unroll
;                 for (int m = 0; m < 4; ++m)
; #pragma unroll
;                     for (int n = 0; n < 2; ++n) acc[a][b][m][n] = (f32x4){0.f, 0.f, 0.f, 0.f};
;         cur = nxt; cA = nA; cB = nB; ++ui;
.LBB0_495:
	s_and_b64 s[24:25], s[20:21], exec
	s_cselect_b32 s33, s17, s5
	s_cselect_b32 s57, s16, s4
	s_cselect_b32 s58, s19, s23
	s_cselect_b32 s59, s18, s22
	s_add_i32 s60, s56, -2
	s_add_u32 s61, s22, 0x100
	v_mov_b32_e32 v0, 0
	s_addc_u32 s62, s23, 0
	s_mov_b32 s24, 0
	v_mov_b32_e32 v1, v0
	v_pk_mov_b32 v[2:3], v[0:1], v[0:1] op_sel:[0,0]
	v_pk_mov_b32 v[4:5], v[0:1], v[0:1] op_sel:[0,0]
	v_pk_mov_b32 v[6:7], v[0:1], v[0:1] op_sel:[0,0]
	v_pk_mov_b32 v[8:9], v[0:1], v[0:1] op_sel:[0,0]
	v_pk_mov_b32 v[10:11], v[0:1], v[0:1] op_sel:[0,0]
	v_pk_mov_b32 v[12:13], v[0:1], v[0:1] op_sel:[0,0]
	v_pk_mov_b32 v[14:15], v[0:1], v[0:1] op_sel:[0,0]
	v_pk_mov_b32 v[24:25], v[0:1], v[0:1] op_sel:[0,0]
	v_pk_mov_b32 v[26:27], v[0:1], v[0:1] op_sel:[0,0]
	v_pk_mov_b32 v[28:29], v[0:1], v[0:1] op_sel:[0,0]
	v_pk_mov_b32 v[30:31], v[0:1], v[0:1] op_sel:[0,0]
	v_pk_mov_b32 v[40:41], v[0:1], v[0:1] op_sel:[0,0]
	v_pk_mov_b32 v[42:43], v[0:1], v[0:1] op_sel:[0,0]
	v_pk_mov_b32 v[44:45], v[0:1], v[0:1] op_sel:[0,0]
	v_pk_mov_b32 v[46:47], v[0:1], v[0:1] op_sel:[0,0]
	v_pk_mov_b32 v[16:17], v[0:1], v[0:1] op_sel:[0,0]
	v_pk_mov_b32 v[18:19], v[0:1], v[0:1] op_sel:[0,0]
	v_pk_mov_b32 v[20:21], v[0:1], v[0:1] op_sel:[0,0]
	v_pk_mov_b32 v[22:23], v[0:1], v[0:1] op_sel:[0,0]
	v_pk_mov_b32 v[32:33], v[0:1], v[0:1] op_sel:[0,0]
	v_pk_mov_b32 v[34:35], v[0:1], v[0:1] op_sel:[0,0]
	v_pk_mov_b32 v[36:37], v[0:1], v[0:1] op_sel:[0,0]
	v_pk_mov_b32 v[38:39], v[0:1], v[0:1] op_sel:[0,0]
	v_pk_mov_b32 v[48:49], v[0:1], v[0:1] op_sel:[0,0]
	v_pk_mov_b32 v[50:51], v[0:1], v[0:1] op_sel:[0,0]
	v_pk_mov_b32 v[52:53], v[0:1], v[0:1] op_sel:[0,0]
	v_pk_mov_b32 v[54:55], v[0:1], v[0:1] op_sel:[0,0]
	v_pk_mov_b32 v[56:57], v[0:1], v[0:1] op_sel:[0,0]
	v_pk_mov_b32 v[58:59], v[0:1], v[0:1] op_sel:[0,0]
	v_pk_mov_b32 v[60:61], v[0:1], v[0:1] op_sel:[0,0]
	v_pk_mov_b32 v[62:63], v[0:1], v[0:1] op_sel:[0,0]
	v_pk_mov_b32 v[64:65], v[0:1], v[0:1] op_sel:[0,0]
	v_pk_mov_b32 v[66:67], v[0:1], v[0:1] op_sel:[0,0]
	v_pk_mov_b32 v[68:69], v[0:1], v[0:1] op_sel:[0,0]
	v_pk_mov_b32 v[70:71], v[0:1], v[0:1] op_sel:[0,0]
	v_pk_mov_b32 v[72:73], v[0:1], v[0:1] op_sel:[0,0]
	v_pk_mov_b32 v[74:75], v[0:1], v[0:1] op_sel:[0,0]
	v_pk_mov_b32 v[76:77], v[0:1], v[0:1] op_sel:[0,0]
	v_pk_mov_b32 v[78:79], v[0:1], v[0:1] op_sel:[0,0]
	v_pk_mov_b32 v[88:89], v[0:1], v[0:1] op_sel:[0,0]
	v_pk_mov_b32 v[90:91], v[0:1], v[0:1] op_sel:[0,0]
	v_pk_mov_b32 v[92:93], v[0:1], v[0:1] op_sel:[0,0]
	v_pk_mov_b32 v[94:95], v[0:1], v[0:1] op_sel:[0,0]
	v_pk_mov_b32 v[104:105], v[0:1], v[0:1] op_sel:[0,0]
	v_pk_mov_b32 v[106:107], v[0:1], v[0:1] op_sel:[0,0]
	v_pk_mov_b32 v[108:109], v[0:1], v[0:1] op_sel:[0,0]
	v_pk_mov_b32 v[110:111], v[0:1], v[0:1] op_sel:[0,0]
	v_pk_mov_b32 v[80:81], v[0:1], v[0:1] op_sel:[0,0]
	v_pk_mov_b32 v[82:83], v[0:1], v[0:1] op_sel:[0,0]
	v_pk_mov_b32 v[84:85], v[0:1], v[0:1] op_sel:[0,0]
	v_pk_mov_b32 v[86:87], v[0:1], v[0:1] op_sel:[0,0]
	v_pk_mov_b32 v[96:97], v[0:1], v[0:1] op_sel:[0,0]
	v_pk_mov_b32 v[98:99], v[0:1], v[0:1] op_sel:[0,0]
	v_pk_mov_b32 v[100:101], v[0:1], v[0:1] op_sel:[0,0]
	v_pk_mov_b32 v[102:103], v[0:1], v[0:1] op_sel:[0,0]
	v_pk_mov_b32 v[112:113], v[0:1], v[0:1] op_sel:[0,0]
	v_pk_mov_b32 v[114:115], v[0:1], v[0:1] op_sel:[0,0]
	v_pk_mov_b32 v[116:117], v[0:1], v[0:1] op_sel:[0,0]
	v_pk_mov_b32 v[118:119], v[0:1], v[0:1] op_sel:[0,0]
	v_pk_mov_b32 v[122:123], v[0:1], v[0:1] op_sel:[0,0]
	v_pk_mov_b32 v[124:125], v[0:1], v[0:1] op_sel:[0,0]
	v_pk_mov_b32 v[126:127], v[0:1], v[0:1] op_sel:[0,0]
	v_pk_mov_b32 v[128:129], v[0:1], v[0:1] op_sel:[0,0]

;     __device__ __forceinline__ bool next(int i, UnitD& u) const { Unit t; if (!so.next(i, t)) return false; u.A = A + (size_t)t.pm * tsA; u.B = B + (size_t)t.pn * tsB; u.nt = nt; u.pm = t.pm; u.pn = t.pn; u.tag = 0; return true; }
; template <class Epi, class Sched>
; __device__ __forceinline__ void gemm_stream(LAS unsigned char* lds, const int lda, const int ldb, const Sched& S, const Epi& E, const int wv) {
;     ...
;     for (;;) {
;         const bool has_next = S.next(ui + 1, nxt);
;         const char* nA = has_next ? nxt.A : cA; const char* nB = has_next ? nxt.B : cB;
;         const int nt = cur.nt;
;         for (int t = 0; t < nt; t += 2) {
;             const bool last = (t == nt - 2);
;             const char* a1 = cA + (size_t)(t + 1) * kstep;
;             const char* a2 = last ? nA : cA + (size_t)(t + 2) * kstep; const char* b2 = last ? nB : cB + (size_t)(t + 2) * kstep;
;             const char* a3 = a2 + kstep; const char* b3 = b2 + kstep;
;     ...
; #pragma unroll
;         for (int a = 0; a < 2; ++a)
; #pragma unroll
;             for (int b = 0; b < 2; ++b)
; #pragma unroll
;                 for (int m = 0; m < 4; ++m)
; #pragma unroll
;                     for (int n = 0; n < 2; ++n) acc[a][b][m][n] = (f32x4){0.f, 0.f, 0.f, 0.f};
;         cur = nxt; cA = nA; cB = nB; ++ui;
.LBB0_599:
	s_add_u32 s20, s20, 0x80080
	s_addc_u32 s21, s21, 0
	s_add_u32 s13, s22, 0x100
	v_mov_b32_e32 v0, 0
	s_addc_u32 s15, s23, 0
	s_mov_b32 s46, -2
	v_mov_b32_e32 v1, v0
	v_pk_mov_b32 v[2:3], v[0:1], v[0:1] op_sel:[0,0]
	v_pk_mov_b32 v[4:5], v[0:1], v[0:1] op_sel:[0,0]
	v_pk_mov_b32 v[6:7], v[0:1], v[0:1] op_sel:[0,0]
	v_pk_mov_b32 v[16:17], v[0:1], v[0:1] op_sel:[0,0]
	v_pk_mov_b32 v[18:19], v[0:1], v[0:1] op_sel:[0,0]
	v_pk_mov_b32 v[20:21], v[0:1], v[0:1] op_sel:[0,0]
	v_pk_mov_b32 v[22:23], v[0:1], v[0:1] op_sel:[0,0]
	v_pk_mov_b32 v[32:33], v[0:1], v[0:1] op_sel:[0,0]
	v_pk_mov_b32 v[34:35], v[0:1], v[0:1] op_sel:[0,0]
	v_pk_mov_b32 v[36:37], v[0:1], v[0:1] op_sel:[0,0]
	v_pk_mov_b32 v[38:39], v[0:1], v[0:1] op_sel:[0,0]
	v_pk_mov_b32 v[48:49], v[0:1], v[0:1] op_sel:[0,0]
	v_pk_mov_b32 v[50:51], v[0:1], v[0:1] op_sel:[0,0]
	v_pk_mov_b32 v[52:53], v[0:1], v[0:1] op_sel:[0,0]
	v_pk_mov_b32 v[54:55], v[0:1], v[0:1] op_sel:[0,0]
	v_pk_mov_b32 v[8:9], v[0:1], v[0:1] op_sel:[0,0]
	v_pk_mov_b32 v[10:11], v[0:1], v[0:1] op_sel:[0,0]
	v_pk_mov_b32 v[12:13], v[0:1], v[0:1] op_sel:[0,0]
	v_pk_mov_b32 v[14:15], v[0:1], v[0:1] op_sel:[0,0]
	v_pk_mov_b32 v[24:25], v[0:1], v[0:1] op_sel:[0,0]
	v_pk_mov_b32 v[26:27], v[0:1], v[0:1] op_sel:[0,0]
	v_pk_mov_b32 v[28:29], v[0:1], v[0:1] op_sel:[0,0]
	v_pk_mov_b32 v[30:31], v[0:1], v[0:1] op_sel:[0,0]
	v_pk_mov_b32 v[40:41], v[0:1], v[0:1] op_sel:[0,0]
	v_pk_mov_b32 v[42:43], v[0:1], v[0:1] op_sel:[0,0]
	v_pk_mov_b32 v[44:45], v[0:1], v[0:1] op_sel:[0,0]
	v_pk_mov_b32 v[46:47], v[0:1], v[0:1] op_sel:[0,0]
	v_pk_mov_b32 v[56:57], v[0:1], v[0:1] op_sel:[0,0]
	v_pk_mov_b32 v[58:59], v[0:1], v[0:1] op_sel:[0,0]
	v_pk_mov_b32 v[60:61], v[0:1], v[0:1] op_sel:[0,0]
	v_pk_mov_b32 v[62:63], v[0:1], v[0:1] op_sel:[0,0]
	v_pk_mov_b32 v[64:65], v[0:1], v[0:1] op_sel:[0,0]
	v_pk_mov_b32 v[66:67], v[0:1], v[0:1] op_sel:[0,0]
	v_pk_mov_b32 v[68:69], v[0:1], v[0:1] op_sel:[0,0]
	v_pk_mov_b32 v[70:71], v[0:1], v[0:1] op_sel:[0,0]
	v_pk_mov_b32 v[80:81], v[0:1], v[0:1] op_sel:[0,0]
	v_pk_mov_b32 v[82:83], v[0:1], v[0:1] op_sel:[0,0]
	v_pk_mov_b32 v[84:85], v[0:1], v[0:1] op_sel:[0,0]
	v_pk_mov_b32 v[86:87], v[0:1], v[0:1] op_sel:[0,0]
	v_pk_mov_b32 v[96:97], v[0:1], v[0:1] op_sel:[0,0]
	v_pk_mov_b32 v[98:99], v[0:1], v[0:1] op_sel:[0,0]
	v_pk_mov_b32 v[100:101], v[0:1], v[0:1] op_sel:[0,0]
	v_pk_mov_b32 v[102:103], v[0:1], v[0:1] op_sel:[0,0]
	v_pk_mov_b32 v[112:113], v[0:1], v[0:1] op_sel:[0,0]
	v_pk_mov_b32 v[114:115], v[0:1], v[0:1] op_sel:[0,0]
	v_pk_mov_b32 v[116:117], v[0:1], v[0:1] op_sel:[0,0]
	v_pk_mov_b32 v[118:119], v[0:1], v[0:1] op_sel:[0,0]
	v_pk_mov_b32 v[72:73], v[0:1], v[0:1] op_sel:[0,0]
	v_pk_mov_b32 v[74:75], v[0:1], v[0:1] op_sel:[0,0]
	v_pk_mov_b32 v[76:77], v[0:1], v[0:1] op_sel:[0,0]
	v_pk_mov_b32 v[78:79], v[0:1], v[0:1] op_sel:[0,0]
	v_pk_mov_b32 v[88:89], v[0:1], v[0:1] op_sel:[0,0]
	v_pk_mov_b32 v[90:91], v[0:1], v[0:1] op_sel:[0,0]
	v_pk_mov_b32 v[92:93], v[0:1], v[0:1] op_sel:[0,0]
	v_pk_mov_b32 v[94:95], v[0:1], v[0:1] op_sel:[0,0]
	v_pk_mov_b32 v[104:105], v[0:1], v[0:1] op_sel:[0,0]
	v_pk_mov_b32 v[106:107], v[0:1], v[0:1] op_sel:[0,0]
	v_pk_mov_b32 v[108:109], v[0:1], v[0:1] op_sel:[0,0]
	v_pk_mov_b32 v[110:111], v[0:1], v[0:1] op_sel:[0,0]
	v_pk_mov_b32 v[120:121], v[0:1], v[0:1] op_sel:[0,0]
	v_pk_mov_b32 v[122:123], v[0:1], v[0:1] op_sel:[0,0]
	v_pk_mov_b32 v[124:125], v[0:1], v[0:1] op_sel:[0,0]
	v_pk_mov_b32 v[126:127], v[0:1], v[0:1] op_sel:[0,0]
